# bias hoist + adaLN layers1-3 deferred into P4 idle (reduction in P6) + pooling moved into P2 slack
# speedup vs baseline: 1.0055x; 1.0055x over previous
; #define GAS __attribute__((address_space(1)))
; __device__ __forceinline__ float silu_f(float v) { return v / (1.0f + __expf(-v)); }
; __device__ __forceinline__ void pro_a(Frame& F, CArgs a, unsigned long long& tm_acc) {
;     ...
;     {
;         GAS float* modp = (GAS float*)(ws + WS_MODP);
;         for (int it = gw; it < DEPTH * 48 * 32; it += NGW) {
;             const int ks = it & 31, cb = (it >> 5) % 48, l = it / (32 * 48);
;             const int col = cb * 256 + lane * 4, k0 = ks * 64;
;             float sv[5];
; #pragma unroll
;             for (int b = 0; b < 5; ++b) { const GAS float* cp = b < 4 ? ((const GAS float*)a->in[I_C]) + b * D : ((const GAS float*)a->in[I_CCTX]); sv[b] = silu_f(cp[k0 + lane]); }
;             f32x4 acc[5];
; #pragma unroll
;             for (int b = 0; b < 5; ++b) acc[b] = (f32x4){0.f, 0.f, 0.f, 0.f};
;             const GAS float* wp = ((const GAS float*)a->in[I_WADA]) + ((size_t)l * D + k0) * 12288 + col;
.LBB0_1228:
	s_cmpk_lt_i32 s2, 32
	s_cbranch_scc1 .Lad_skip
	v_readlane_b32 s100, v255, 42
	s_nop 3
	s_cmp_gt_u32 s100, 2
	s_cbranch_scc1 .Lad_skip
	v_writelane_b32 v200, s4, 0
	v_writelane_b32 v200, s5, 1
	v_writelane_b32 v200, s6, 2
	v_writelane_b32 v200, s7, 3
	v_writelane_b32 v200, s8, 4
	v_writelane_b32 v200, s9, 5
	v_writelane_b32 v200, s10, 6
	v_writelane_b32 v200, s11, 7
	v_writelane_b32 v200, s12, 8
	v_writelane_b32 v200, s13, 9
	v_writelane_b32 v200, s14, 10
	v_writelane_b32 v200, s15, 11
	v_writelane_b32 v200, s16, 12
	v_writelane_b32 v200, s17, 13
	v_writelane_b32 v200, s18, 14
	v_writelane_b32 v200, s19, 15
	v_writelane_b32 v200, s20, 16
	v_writelane_b32 v200, s21, 17
	v_writelane_b32 v200, s22, 18
	v_writelane_b32 v200, s23, 19
	v_writelane_b32 v200, s24, 20
	v_writelane_b32 v200, s25, 21
	v_writelane_b32 v200, s26, 22
	v_writelane_b32 v200, s27, 23
	v_writelane_b32 v200, s28, 24
	v_writelane_b32 v200, s29, 25
	v_writelane_b32 v200, s30, 26
	v_writelane_b32 v200, s31, 27
	v_writelane_b32 v200, s32, 28
	v_writelane_b32 v200, s33, 29
	v_writelane_b32 v200, s34, 30
	v_writelane_b32 v200, s35, 31
	v_writelane_b32 v200, s36, 32
	v_writelane_b32 v200, s37, 33
	v_writelane_b32 v200, s38, 34
	v_writelane_b32 v200, s39, 35
	v_writelane_b32 v200, s40, 36
	v_writelane_b32 v200, s41, 37
	v_writelane_b32 v200, s42, 38
	v_writelane_b32 v200, s43, 39
	v_writelane_b32 v200, s44, 40
	v_writelane_b32 v200, s45, 41
	v_writelane_b32 v200, s46, 42
	v_writelane_b32 v200, s47, 43
	v_writelane_b32 v200, s48, 44
	v_writelane_b32 v200, s49, 45
	v_writelane_b32 v200, s50, 46
	v_writelane_b32 v200, s51, 47
	v_writelane_b32 v200, s52, 48
	v_writelane_b32 v200, s53, 49
	s_load_dwordx2 s[36:37], s[0:1], 0x130
	v_readfirstlane_b32 s19, v0
	v_and_b32_e32 v130, 63, v0
	s_lshr_b32 s4, s19, 6
	s_lshl_b32 s17, s2, 3
	s_addk_i32 s17, 0xff00
	s_add_i32 s5, s100, 1
	s_mulk_i32 s5, 0x600
	s_add_i32 s17, s17, s5
	s_add_i32 s18, s17, s4
	s_add_i32 s101, s5, 0x5ff
	s_movk_i32 s16, 0x700
	v_lshlrev_b32_e32 v130, 2, v130
	s_waitcnt lgkmcnt(0)
	s_cmp_gt_i32 s18, s101
	s_cbranch_scc1 .Lad_exit
	s_load_dwordx2 s[22:23], s[0:1], 0x8
	s_load_dwordx4 s[12:15], s[0:1], 0x18
	s_add_u32 s20, s36, 0x48000000
	s_addc_u32 s21, s37, 0
	s_lshr_b32 s4, s19, 6
	s_waitcnt lgkmcnt(0)
	s_add_u32 s24, s22, 0x2000
	s_addc_u32 s25, s23, 0
	s_add_u32 s26, s22, 0x4000
	s_addc_u32 s27, s23, 0
	s_waitcnt vmcnt(23)
	v_mbcnt_lo_u32_b32 v2, -1, 0
	s_add_u32 s38, s22, 0x6000
	v_mbcnt_hi_u32_b32 v2, -1, v2
	s_addc_u32 s39, s23, 0
	v_lshlrev_b32_e32 v2, 2, v2
	s_add_u32 s19, s14, 0x30000
	s_waitcnt vmcnt(17)
	v_and_b32_e32 v28, 0x100, v2
	s_addc_u32 s40, s15, 0
	s_add_i32 s17, s17, s4
	s_mov_b32 s41, 0xfffd0000
	s_mov_b32 s42, 0xfffdc000
	s_mov_b32 s43, 0xfffe8000
	s_mov_b32 s44, 0xffff4000
	s_mov_b32 s45, 0xc000
	s_mov_b32 s46, 0x18000
	s_mov_b32 s47, 0x24000
	s_mov_b64 s[14:15], 0x60000
	v_mov_b32_e32 v29, 0x3c000
	s_mov_b32 s48, s18

; __device__ __forceinline__ void xcd_barrier(const XcdBarrier& b) {
;     asm volatile("s_waitcnt vmcnt(0)" ::: "memory");
;     __syncthreads();
;     if (threadIdx.x == 0) {
;         unsigned* bar = b.bar;
;         __builtin_amdgcn_s_waitcnt(0);
;         unsigned nloc = b.st[0], nx = b.st[1];
;         if (nloc == 0u) { xcd_barrier_complete(bar, b.x, nloc, nx); b.st[0] = nloc; b.st[1] = nx; }
.Lad_exit:
	s_nop 0
	v_readlane_b32 s4, v200, 0
	v_readlane_b32 s5, v200, 1
	v_readlane_b32 s6, v200, 2
	v_readlane_b32 s7, v200, 3
	v_readlane_b32 s8, v200, 4
	v_readlane_b32 s9, v200, 5
	v_readlane_b32 s10, v200, 6
	v_readlane_b32 s11, v200, 7
	v_readlane_b32 s12, v200, 8
	v_readlane_b32 s13, v200, 9
	v_readlane_b32 s14, v200, 10
	v_readlane_b32 s15, v200, 11
	v_readlane_b32 s16, v200, 12
	v_readlane_b32 s17, v200, 13
	v_readlane_b32 s18, v200, 14
	v_readlane_b32 s19, v200, 15
	v_readlane_b32 s20, v200, 16
	v_readlane_b32 s21, v200, 17
	v_readlane_b32 s22, v200, 18
	v_readlane_b32 s23, v200, 19
	v_readlane_b32 s24, v200, 20
	v_readlane_b32 s25, v200, 21
	v_readlane_b32 s26, v200, 22
	v_readlane_b32 s27, v200, 23
	v_readlane_b32 s28, v200, 24
	v_readlane_b32 s29, v200, 25
	v_readlane_b32 s30, v200, 26
	v_readlane_b32 s31, v200, 27
	v_readlane_b32 s32, v200, 28
	v_readlane_b32 s33, v200, 29
	v_readlane_b32 s34, v200, 30
	v_readlane_b32 s35, v200, 31
	v_readlane_b32 s36, v200, 32
	v_readlane_b32 s37, v200, 33
	v_readlane_b32 s38, v200, 34
	v_readlane_b32 s39, v200, 35
	v_readlane_b32 s40, v200, 36
	v_readlane_b32 s41, v200, 37
	v_readlane_b32 s42, v200, 38
	v_readlane_b32 s43, v200, 39
	v_readlane_b32 s44, v200, 40
	v_readlane_b32 s45, v200, 41
	v_readlane_b32 s46, v200, 42
	v_readlane_b32 s47, v200, 43
	v_readlane_b32 s48, v200, 44
	v_readlane_b32 s49, v200, 45
	v_readlane_b32 s50, v200, 46
	v_readlane_b32 s51, v200, 47
	v_readlane_b32 s52, v200, 48
	v_readlane_b32 s53, v200, 49
	s_nop 3
.Lad_skip:
	v_readlane_b32 s4, v255, 44
	s_add_i32 s4, s4, 8
	s_cmp_lt_i32 s4, s97
	s_cselect_b64 s[6:7], -1, 0
	s_and_b64 s[8:9], s[22:23], s[6:7]
	s_andn2_b64 vcc, exec, s[8:9]
	s_cbranch_vccnz .LBB0_1282
	s_waitcnt vmcnt(0)
	s_waitcnt vmcnt(0)
	s_barrier
	s_and_saveexec_b64 s[8:9], s[88:89]
	s_cbranch_execz .LBB0_1281
	v_readlane_b32 s5, v255, 28
	s_waitcnt vmcnt(0) expcnt(0) lgkmcnt(0)
	s_nop 0
	v_mov_b32_e32 v1, s5
	ds_read_b32 v3, v1
	v_readlane_b32 s5, v255, 29
	s_waitcnt lgkmcnt(0)
	v_cmp_ne_u32_e32 vcc, 0, v3
	v_mov_b32_e32 v1, s5
	ds_read_b32 v2, v1
	s_cbranch_vccnz .LBB0_1245
	v_readlane_b32 s12, v253, 0
	v_readlane_b32 s13, v253, 1
	s_load_dwordx2 s[10:11], s[12:13], 0x4
	s_mov_b32 s22, 1
	s_waitcnt lgkmcnt(0)
	s_mul_i32 s5, s10, s3
	s_mul_i32 s5, s5, s11
	s_branch .LBB0_1233

; #define GAS __attribute__((address_space(1)))
; __device__ __forceinline__ void pro_b(Frame& F, CArgs a) {
;     const GAS float* modp = (const GAS float*)(F.ws + WS_MODP); GAS float* mod = (GAS float*)(F.ws + WS_MOD);
;     for (int e = F.blk * 512 + F.tid; e < DEPTH * 5 * 12288; e += F.G * 512) {
;         const int j = e % 12288, l = e / (5 * 12288);
;         float s = ((const GAS float*)a->in[I_BADA])[l * 12288 + j];
; #pragma unroll 8
;         for (int ks = 0; ks < 32; ++ks) s += modp[(size_t)ks * DEPTH * 5 * 12288 + e];
;         mod[e] = s;
;     }
.LBB0_1424:
	s_barrier
.LBB0_1425:
	v_readlane_b32 s100, v255, 42
	s_nop 3
	s_cmp_gt_u32 s100, 2
	s_cbranch_scc1 .Lmr_skip
	v_writelane_b32 v200, s4, 0
	v_writelane_b32 v200, s5, 1
	v_writelane_b32 v200, s6, 2
	v_writelane_b32 v200, s7, 3
	v_writelane_b32 v200, s8, 4
	v_writelane_b32 v200, s9, 5
	v_writelane_b32 v200, s10, 6
	v_writelane_b32 v200, s11, 7
	v_writelane_b32 v200, s12, 8
	v_writelane_b32 v200, s13, 9
	v_writelane_b32 v200, s14, 10
	v_writelane_b32 v200, s15, 11
	v_writelane_b32 v200, s16, 12
	v_writelane_b32 v200, s17, 13
	v_writelane_b32 v200, s18, 14
	v_writelane_b32 v200, s19, 15
	v_writelane_b32 v200, s20, 16
	v_writelane_b32 v200, s21, 17
	v_writelane_b32 v200, s22, 18
	v_writelane_b32 v200, s23, 19
	s_add_i32 s100, s100, 1
	s_mul_i32 s100, s100, 0xf000
	s_add_i32 s101, s100, 0xf000
	s_mov_b32 s4, s101
	v_lshl_add_u32 v2, s2, 9, v0
	v_add_u32_e32 v2, s100, v2
	s_load_dwordx2 s[14:15], s[0:1], 0x130
	v_cmp_gt_i32_e32 vcc, s4, v2
	s_waitcnt lgkmcnt(0)
	s_and_saveexec_b64 s[4:5], vcc
	s_cbranch_execz .Lmr_331
	s_load_dwordx2 s[12:13], s[0:1], 0x28
	s_lshl_b32 s8, s3, 9
	s_add_u32 s10, s14, 0x100000
	s_addc_u32 s11, s15, 0
	v_ashrrev_i32_e32 v3, 31, v2
	s_ashr_i32 s9, s8, 31
	v_lshl_add_u64 v[4:5], v[2:3], 2, s[14:15]
	s_lshl_b64 s[14:15], s[8:9], 2
	s_mov_b64 s[16:17], 0
	s_mov_b32 s9, 0x2aaaaaab
	s_movk_i32 s20, 0x3000
	s_mov_b32 s21, 0x88888889
	s_add_i32 s22, s101, -1

; #define GAS __attribute__((address_space(1)))
; __device__ __forceinline__ void xcd_barrier(const XcdBarrier& b) {
;     asm volatile("s_waitcnt vmcnt(0)" ::: "memory");
;     __syncthreads();
;     if (threadIdx.x == 0) {
;         unsigned* bar = b.bar;
;         __builtin_amdgcn_s_waitcnt(0);
;         unsigned nloc = b.st[0], nx = b.st[1];
;         if (nloc == 0u) { xcd_barrier_complete(bar, b.x, nloc, nx); b.st[0] = nloc; b.st[1] = nx; }
; __device__ __forceinline__ void pro_b(Frame& F, CArgs a) {
;     ...
;     for (int e = F.blk * 512 + F.tid; e < DEPTH * 5 * 12288; e += F.G * 512) {
;         const int j = e % 12288, l = e / (5 * 12288);
;         float s = ((const GAS float*)a->in[I_BADA])[l * 12288 + j];
; #pragma unroll 8
;         for (int ks = 0; ks < 32; ++ks) s += modp[(size_t)ks * DEPTH * 5 * 12288 + e];
;         mod[e] = s;
;     }
.Lmr_329:
	v_lshl_add_u64 v[6:7], v[4:5], 0, s[18:19]
	v_add_co_u32_e32 v8, vcc, 0x48000000, v6
	s_add_u32 s18, s18, 0x780000
	s_nop 0
	v_addc_co_u32_e32 v9, vcc, 0, v7, vcc
	s_waitcnt vmcnt(22)
	v_add_co_u32_e32 v10, vcc, 0x480f0000, v6
	s_addc_u32 s19, s19, 0
	s_nop 0
	v_addc_co_u32_e32 v11, vcc, 0, v7, vcc
	v_add_co_u32_e32 v12, vcc, 0x481e0000, v6
	global_load_dword v3, v[8:9], off
	global_load_dword v14, v[10:11], off
	v_addc_co_u32_e32 v13, vcc, 0, v7, vcc
	v_add_co_u32_e32 v8, vcc, 0x482d0000, v6
	s_cmp_eq_u32 s18, 0x1e00000
	s_nop 0
	v_addc_co_u32_e32 v9, vcc, 0, v7, vcc
	v_add_co_u32_e32 v10, vcc, 0x483c0000, v6
	global_load_dword v15, v[12:13], off
	global_load_dword v16, v[8:9], off
	v_addc_co_u32_e32 v11, vcc, 0, v7, vcc
	v_add_co_u32_e32 v8, vcc, 0x484b0000, v6
	s_waitcnt vmcnt(3)
	v_add_f32_e32 v1, v1, v3
	v_addc_co_u32_e32 v9, vcc, 0, v7, vcc
	v_add_co_u32_e32 v12, vcc, 0x485a0000, v6
	global_load_dword v17, v[10:11], off
	global_load_dword v18, v[8:9], off
	v_addc_co_u32_e32 v13, vcc, 0, v7, vcc
	v_add_co_u32_e32 v6, vcc, 0x48690000, v6
	s_waitcnt vmcnt(4)
	v_add_f32_e32 v1, v1, v14
	v_addc_co_u32_e32 v7, vcc, 0, v7, vcc
	global_load_dword v8, v[12:13], off
	global_load_dword v9, v[6:7], off
	s_waitcnt vmcnt(5)
	v_add_f32_e32 v1, v1, v15
	s_waitcnt vmcnt(4)
	v_add_f32_e32 v1, v1, v16
	s_waitcnt vmcnt(3)
	v_add_f32_e32 v1, v1, v17
	s_waitcnt vmcnt(2)
	v_add_f32_e32 v1, v1, v18
	s_waitcnt vmcnt(1)
	v_add_f32_e32 v1, v1, v8
	s_waitcnt vmcnt(0)
	v_add_f32_e32 v1, v1, v9
	s_cbranch_scc0 .Lmr_329
	v_ashrrev_i32_e32 v3, 31, v2
	v_lshl_add_u64 v[6:7], v[2:3], 2, s[10:11]
	v_add_u32_e32 v2, s8, v2
	v_cmp_lt_i32_e32 vcc, s22, v2
	s_or_b64 s[16:17], vcc, s[16:17]
	v_lshl_add_u64 v[4:5], v[4:5], 0, s[14:15]
	global_store_dword v[6:7], v1, off
	s_andn2_b64 exec, exec, s[16:17]
	s_cbranch_execnz .Lmr_328
.Lmr_331:
	s_or_b64 exec, exec, s[4:5]
	s_nop 0
	v_readlane_b32 s4, v200, 0
	v_readlane_b32 s5, v200, 1
	v_readlane_b32 s6, v200, 2
	v_readlane_b32 s7, v200, 3
	v_readlane_b32 s8, v200, 4
	v_readlane_b32 s9, v200, 5
	v_readlane_b32 s10, v200, 6
	v_readlane_b32 s11, v200, 7
	v_readlane_b32 s12, v200, 8
	v_readlane_b32 s13, v200, 9
	v_readlane_b32 s14, v200, 10
	v_readlane_b32 s15, v200, 11
	v_readlane_b32 s16, v200, 12
	v_readlane_b32 s17, v200, 13
	v_readlane_b32 s18, v200, 14
	v_readlane_b32 s19, v200, 15
	v_readlane_b32 s20, v200, 16
	v_readlane_b32 s21, v200, 17
	v_readlane_b32 s22, v200, 18
	v_readlane_b32 s23, v200, 19
	s_nop 3
.Lmr_skip:
	v_readlane_b32 s4, v255, 44
	s_add_i32 s4, s4, 10
	s_cmp_lt_i32 s4, s97
	s_cselect_b64 s[8:9], -1, 0
	s_and_b64 s[6:7], s[6:7], s[8:9]
	s_andn2_b64 vcc, exec, s[6:7]
	s_cbranch_vccnz .LBB0_1479
	s_waitcnt vmcnt(0)
	s_waitcnt vmcnt(0)
	s_barrier
	s_and_saveexec_b64 s[6:7], s[88:89]
	s_cbranch_execz .LBB0_1478
	v_readlane_b32 s5, v255, 28
	s_waitcnt vmcnt(0) expcnt(0) lgkmcnt(0)
	s_nop 0
	v_mov_b32_e32 v1, s5
	ds_read_b32 v3, v1
	v_readlane_b32 s5, v255, 29
	s_waitcnt lgkmcnt(0)
	v_cmp_ne_u32_e32 vcc, 0, v3
	v_mov_b32_e32 v1, s5
	ds_read_b32 v2, v1
	s_cbranch_vccnz .LBB0_1442
	v_readlane_b32 s12, v253, 0
	v_readlane_b32 s13, v253, 1
	s_load_dwordx2 s[10:11], s[12:13], 0x4
	s_mov_b32 s22, 1
	s_waitcnt lgkmcnt(0)
	s_mul_i32 s5, s10, s3
	s_mul_i32 s5, s5, s11
	s_branch .LBB0_1430
